# norm-scaled weight conversion tiles (q / kv up-projection): 16 row loads in flight instead of two at a time
# baseline (speedup 1.0000x reference)
; DI int tidx() { int t = __builtin_amdgcn_workitem_id_x(); asm volatile("" : "+v"(t)); return t; }
; DI float wsrc(KP p, int job, int l, int k, int n) {
;     ...
;     case J_WUKV: return p->w_ukv[((size_t)l * 256 + k) * 1024 + n] * p->kv_norm_g[l * 256 + k];
; DI void conv_tile(KP p, u16* dst, int K, int job, int l, int nt, int kt, char* smem) {
;   float* tile = (float*)smem;
;   const int tid = tidx();
;   __syncthreads();
;   {
;     const int n = nt * 64 + (tid & 63), kb = kt * 64 + (tid >> 6) * 16;
; #pragma unroll
;     for (int i = 0; i < 16; ++i) tile[((tid >> 6) * 16 + i) * 65 + (tid & 63)] = wsrc(p, job, l, kb + i, n);
;   }
;   __syncthreads();
.LBB0_226:
	s_andn2_b64 vcc, exec, s[8:9]
	s_cbranch_vccnz .LBB0_228
	v_mov_b32_e32 v14, v0
	s_lshl_b32 s2, s35, 4
	s_and_b32 s3, s2, 0x7fc0
	s_lshl_b32 s2, s35, 6
	v_ashrrev_i32_e32 v7, 2, v14
	s_barrier
	s_and_b32 s2, s2, 0xc0
	v_and_b32_e32 v15, -16, v7
	s_load_dwordx4 s[8:11], s[24:25], 0x58
	v_add_u32_e32 v8, s2, v15
	v_ashrrev_i32_e32 v9, 31, v8
	s_addk_i32 s3, 0x9780
	v_and_b32_e32 v2, 63, v14
	v_lshl_add_u64 v[4:5], v[8:9], 0, s[12:13]
	v_or_b32_e32 v198, s3, v2
	v_lshlrev_b64 v[4:5], 12, v[4:5]
	s_waitcnt lgkmcnt(0)
	v_lshl_add_u64 v[4:5], s[10:11], 0, v[4:5]
	v_lshlrev_b64 v[10:11], 2, v[198:199]
	v_or_b32_e32 v28, 1, v8
	v_lshl_add_u64 v[4:5], v[4:5], 0, v[10:11]
	v_ashrrev_i32_e32 v29, 31, v28
	s_mov_b64 vcc, 0x1000
	v_mov_b32_e32 v34, v4
	v_mov_b32_e32 v35, v5
	global_load_dword v36, v[34:35], off
	v_lshl_add_u64 v[34:35], v[34:35], 0, vcc
	global_load_dword v37, v[34:35], off
	v_lshl_add_u64 v[34:35], v[34:35], 0, vcc
	global_load_dword v38, v[34:35], off
	v_lshl_add_u64 v[34:35], v[34:35], 0, vcc
	global_load_dword v39, v[34:35], off
	v_lshl_add_u64 v[34:35], v[34:35], 0, vcc
	global_load_dword v40, v[34:35], off
	v_lshl_add_u64 v[34:35], v[34:35], 0, vcc
	global_load_dword v41, v[34:35], off
	v_lshl_add_u64 v[34:35], v[34:35], 0, vcc
	global_load_dword v42, v[34:35], off
	v_lshl_add_u64 v[34:35], v[34:35], 0, vcc
	global_load_dword v43, v[34:35], off
	v_lshl_add_u64 v[34:35], v[34:35], 0, vcc
	global_load_dword v44, v[34:35], off
	v_lshl_add_u64 v[34:35], v[34:35], 0, vcc
	global_load_dword v45, v[34:35], off
	v_lshl_add_u64 v[34:35], v[34:35], 0, vcc
	global_load_dword v46, v[34:35], off
	v_lshl_add_u64 v[34:35], v[34:35], 0, vcc
	global_load_dword v47, v[34:35], off
	v_lshl_add_u64 v[34:35], v[34:35], 0, vcc
	global_load_dword v48, v[34:35], off
	v_lshl_add_u64 v[34:35], v[34:35], 0, vcc
	global_load_dword v49, v[34:35], off
	v_lshl_add_u64 v[34:35], v[34:35], 0, vcc
	global_load_dword v50, v[34:35], off
	v_lshl_add_u64 v[34:35], v[34:35], 0, vcc
	global_load_dword v51, v[34:35], off
	v_add_u32_e32 v4, s12, v8
	v_lshlrev_b32_e32 v6, 2, v2
	v_mov_b32_e32 v2, s8
	v_mov_b32_e32 v3, s9
	v_ashrrev_i32_e32 v5, 31, v4
	v_lshl_add_u64 v[12:13], v[4:5], 2, v[2:3]
	global_load_dwordx4 v[2:5], v[12:13], off offset:48
	global_load_dwordx4 v[16:19], v[12:13], off offset:32
	global_load_dwordx4 v[20:23], v[12:13], off offset:16
	global_load_dwordx4 v[24:27], v[12:13], off
	v_mad_u64_u32 v[12:13], s[4:5], v15, s54, v[6:7]
	s_lshl_b32 s40, s2, 1
	s_waitcnt vmcnt(0)
	v_mul_f32_e32 v36, v36, v24
	ds_write_b32 v12, v36
	v_mul_f32_e32 v37, v37, v25
	ds_write_b32 v12, v37 offset:260
	v_mul_f32_e32 v38, v38, v26
	ds_write_b32 v12, v38 offset:520
	v_mul_f32_e32 v39, v39, v27
	ds_write_b32 v12, v39 offset:780
	v_mul_f32_e32 v40, v40, v20
	ds_write_b32 v12, v40 offset:1040
	v_mul_f32_e32 v41, v41, v21
	ds_write_b32 v12, v41 offset:1300
	v_mul_f32_e32 v42, v42, v22
	ds_write_b32 v12, v42 offset:1560
	v_mul_f32_e32 v43, v43, v23
	ds_write_b32 v12, v43 offset:1820
	v_mul_f32_e32 v44, v44, v16
	ds_write_b32 v12, v44 offset:2080
	v_mul_f32_e32 v45, v45, v17
	ds_write_b32 v12, v45 offset:2340
	v_mul_f32_e32 v46, v46, v18
	ds_write_b32 v12, v46 offset:2600
	v_mul_f32_e32 v47, v47, v19
	ds_write_b32 v12, v47 offset:2860
	v_mul_f32_e32 v48, v48, v2
	ds_write_b32 v12, v48 offset:3120
	v_mul_f32_e32 v49, v49, v3
	ds_write_b32 v12, v49 offset:3380
	v_mul_f32_e32 v50, v50, v4
	ds_write_b32 v12, v50 offset:3640
	v_mul_f32_e32 v51, v51, v5
	ds_write_b32 v12, v51 offset:3900
	v_lshlrev_b32_e32 v2, 4, v14
	v_and_b32_e32 v15, 48, v2
	v_and_b32_e32 v2, -4, v14
	v_mul_u32_u24_e32 v3, 0x41, v15
	v_lshl_add_u32 v6, v3, 2, v2
	s_waitcnt lgkmcnt(0)
	s_barrier
	ds_read2_b32 v[2:3], v6 offset1:65
	ds_read2_b32 v[4:5], v6 offset0:130 offset1:195
	v_add_u32_e32 v8, 0x400, v6
	v_add_u32_e32 v10, 0x800, v6
	v_add_u32_e32 v6, 0xc00, v6
	s_waitcnt lgkmcnt(1)
	v_cvt_pk_bf16_f32 v2, v2, v3
	s_waitcnt lgkmcnt(0)
	v_cvt_pk_bf16_f32 v3, v4, v5
	ds_read2_b32 v[4:5], v8 offset0:4 offset1:69
	ds_read2_b32 v[8:9], v8 offset0:134 offset1:199
	ds_read2_b32 v[12:13], v6 offset0:142 offset1:207
	v_lshlrev_b32_e32 v198, 1, v15
	s_waitcnt lgkmcnt(2)
	v_cvt_pk_bf16_f32 v4, v4, v5
	s_waitcnt lgkmcnt(1)
	v_cvt_pk_bf16_f32 v5, v8, v9
	ds_read2_b32 v[8:9], v10 offset0:8 offset1:73
	ds_read2_b32 v[10:11], v10 offset0:138 offset1:203
	s_waitcnt lgkmcnt(1)
	v_cvt_pk_bf16_f32 v8, v8, v9
	s_waitcnt lgkmcnt(0)
	v_cvt_pk_bf16_f32 v9, v10, v11
	ds_read2_b32 v[10:11], v6 offset0:12 offset1:77
	v_add_u32_e32 v6, s3, v7
	v_ashrrev_i32_e32 v7, 31, v6
	v_lshlrev_b64 v[6:7], 9, v[6:7]
	v_lshl_add_u64 v[6:7], s[26:27], 0, v[6:7]
	v_lshl_add_u64 v[6:7], v[6:7], 0, s[40:41]
	v_lshl_add_u64 v[6:7], v[6:7], 0, v[198:199]
	s_mov_b64 s[2:3], 0xde60000
	s_waitcnt lgkmcnt(0)
	v_cvt_pk_bf16_f32 v10, v10, v11
	v_cvt_pk_bf16_f32 v11, v12, v13
	v_lshl_add_u64 v[12:13], v[6:7], 0, s[2:3]
	v_add_co_u32_e32 v6, vcc, 0xde60000, v6
	s_nop 1
	v_addc_co_u32_e32 v7, vcc, 0, v7, vcc
	global_store_dwordx4 v[6:7], v[2:5], off
	global_store_dwordx4 v[12:13], v[8:11], off offset:16

; DI int tidx() { int t = __builtin_amdgcn_workitem_id_x(); asm volatile("" : "+v"(t)); return t; }
; DI float wsrc(KP p, int job, int l, int k, int n) {
;     ...
;     case J_WUQ: return p->w_uq[((size_t)l * 384 + k) * 768 + n] * p->q_norm_g[l * 384 + k];
; DI void conv_tile(KP p, u16* dst, int K, int job, int l, int nt, int kt, char* smem) {
;   float* tile = (float*)smem;
;   const int tid = tidx();
;   __syncthreads();
;   {
;     const int n = nt * 64 + (tid & 63), kb = kt * 64 + (tid >> 6) * 16;
; #pragma unroll
;     for (int i = 0; i < 16; ++i) tile[((tid >> 6) * 16 + i) * 65 + (tid & 63)] = wsrc(p, job, l, kb + i, n);
;   }
;   __syncthreads();
.LBB0_229:
	s_andn2_b64 vcc, exec, s[8:9]
	s_cbranch_vccnz .LBB0_231
	s_add_i32 s2, s34, 0xffc0
	s_and_b32 s3, s2, 0xff
	s_mulk_i32 s3, 0xab
	s_bfe_u32 s3, s3, 0x6000a
	v_mov_b32_e32 v18, v0
	s_mul_i32 s4, s3, 6
	s_barrier
	s_load_dwordx4 s[8:11], s[24:25], 0x48
	s_sub_i32 s2, s2, s4
	v_ashrrev_i32_e32 v11, 2, v18
	s_and_b32 s2, s2, 0xff
	v_and_b32_e32 v19, -16, v11
	v_lshl_add_u32 v12, s2, 6, v19
	s_lshl_b32 s3, s3, 6
	v_and_b32_e32 v2, 63, v18
	v_ashrrev_i32_e32 v13, 31, v12
	v_or_b32_e32 v8, s3, v2
	v_lshlrev_b32_e32 v10, 2, v2
	s_waitcnt lgkmcnt(0)
	v_mov_b32_e32 v2, s8
	v_lshl_add_u64 v[4:5], v[12:13], 0, s[14:15]
	v_mov_b64_e32 v[14:15], s[10:11]
	s_movk_i32 s8, 0xc00
	v_mad_u64_u32 v[6:7], s[4:5], v4, s8, v[14:15]
	v_mad_i32_i24 v7, v5, s8, v7
	v_lshlrev_b32_e32 v198, 2, v8
	v_or_b32_e32 v28, 1, v12
	v_lshl_add_u64 v[4:5], v[6:7], 0, v[198:199]
	v_ashrrev_i32_e32 v29, 31, v28
	s_mov_b64 vcc, 0xc00
	v_mov_b32_e32 v34, v4
	v_mov_b32_e32 v35, v5
	global_load_dword v36, v[34:35], off
	v_lshl_add_u64 v[34:35], v[34:35], 0, vcc
	global_load_dword v37, v[34:35], off
	v_lshl_add_u64 v[34:35], v[34:35], 0, vcc
	global_load_dword v38, v[34:35], off
	v_lshl_add_u64 v[34:35], v[34:35], 0, vcc
	global_load_dword v39, v[34:35], off
	v_lshl_add_u64 v[34:35], v[34:35], 0, vcc
	global_load_dword v40, v[34:35], off
	v_lshl_add_u64 v[34:35], v[34:35], 0, vcc
	global_load_dword v41, v[34:35], off
	v_lshl_add_u64 v[34:35], v[34:35], 0, vcc
	global_load_dword v42, v[34:35], off
	v_lshl_add_u64 v[34:35], v[34:35], 0, vcc
	global_load_dword v43, v[34:35], off
	v_lshl_add_u64 v[34:35], v[34:35], 0, vcc
	global_load_dword v44, v[34:35], off
	v_lshl_add_u64 v[34:35], v[34:35], 0, vcc
	global_load_dword v45, v[34:35], off
	v_lshl_add_u64 v[34:35], v[34:35], 0, vcc
	global_load_dword v46, v[34:35], off
	v_lshl_add_u64 v[34:35], v[34:35], 0, vcc
	global_load_dword v47, v[34:35], off
	v_lshl_add_u64 v[34:35], v[34:35], 0, vcc
	global_load_dword v48, v[34:35], off
	v_lshl_add_u64 v[34:35], v[34:35], 0, vcc
	global_load_dword v49, v[34:35], off
	v_lshl_add_u64 v[34:35], v[34:35], 0, vcc
	global_load_dword v50, v[34:35], off
	v_lshl_add_u64 v[34:35], v[34:35], 0, vcc
	global_load_dword v51, v[34:35], off
	v_add_u32_e32 v4, s14, v12
	v_mov_b32_e32 v3, s9
	v_ashrrev_i32_e32 v5, 31, v4
	v_lshl_add_u64 v[16:17], v[4:5], 2, v[2:3]
	global_load_dwordx4 v[2:5], v[16:17], off offset:48
	global_load_dwordx4 v[6:9], v[16:17], off offset:32
	global_load_dwordx4 v[20:23], v[16:17], off offset:16
	global_load_dwordx4 v[24:27], v[16:17], off
	v_mad_u64_u32 v[16:17], s[4:5], v19, s54, v[10:11]
	s_lshl_b32 s40, s2, 7
	s_waitcnt vmcnt(0)
	v_mul_f32_e32 v36, v36, v24
	ds_write_b32 v16, v36
	v_mul_f32_e32 v37, v37, v25
	ds_write_b32 v16, v37 offset:260
	v_mul_f32_e32 v38, v38, v26
	ds_write_b32 v16, v38 offset:520
	v_mul_f32_e32 v39, v39, v27
	ds_write_b32 v16, v39 offset:780
	v_mul_f32_e32 v40, v40, v20
	ds_write_b32 v16, v40 offset:1040
	v_mul_f32_e32 v41, v41, v21
	ds_write_b32 v16, v41 offset:1300
	v_mul_f32_e32 v42, v42, v22
	ds_write_b32 v16, v42 offset:1560
	v_mul_f32_e32 v43, v43, v23
	ds_write_b32 v16, v43 offset:1820
	v_mul_f32_e32 v44, v44, v6
	ds_write_b32 v16, v44 offset:2080
	v_mul_f32_e32 v45, v45, v7
	ds_write_b32 v16, v45 offset:2340
	v_mul_f32_e32 v46, v46, v8
	ds_write_b32 v16, v46 offset:2600
	v_mul_f32_e32 v47, v47, v9
	ds_write_b32 v16, v47 offset:2860
	v_mul_f32_e32 v48, v48, v2
	ds_write_b32 v16, v48 offset:3120
	v_mul_f32_e32 v49, v49, v3
	ds_write_b32 v16, v49 offset:3380
	v_mul_f32_e32 v50, v50, v4
	ds_write_b32 v16, v50 offset:3640
	v_mul_f32_e32 v51, v51, v5
	ds_write_b32 v16, v51 offset:3900
	v_lshlrev_b32_e32 v2, 4, v18
	v_and_b32_e32 v14, 48, v2
	v_and_b32_e32 v2, -4, v18
	v_mul_u32_u24_e32 v3, 0x41, v14
	v_lshl_add_u32 v10, v3, 2, v2
	s_waitcnt lgkmcnt(0)
	s_barrier
	ds_read2_b32 v[2:3], v10 offset1:65
	ds_read2_b32 v[4:5], v10 offset0:130 offset1:195
	v_add_u32_e32 v6, 0x400, v10
	v_add_u32_e32 v8, 0x800, v10
	v_add_u32_e32 v10, 0xc00, v10
	s_waitcnt lgkmcnt(1)
	v_cvt_pk_bf16_f32 v2, v2, v3
	s_waitcnt lgkmcnt(0)
	v_cvt_pk_bf16_f32 v3, v4, v5
	ds_read2_b32 v[4:5], v6 offset0:4 offset1:69
	ds_read2_b32 v[6:7], v6 offset0:134 offset1:199
	ds_read2_b32 v[12:13], v10 offset0:142 offset1:207
	v_lshlrev_b32_e32 v198, 1, v14
	s_waitcnt lgkmcnt(2)
	v_cvt_pk_bf16_f32 v4, v4, v5
	s_waitcnt lgkmcnt(1)
	v_cvt_pk_bf16_f32 v5, v6, v7
	ds_read2_b32 v[6:7], v8 offset0:8 offset1:73
	ds_read2_b32 v[8:9], v8 offset0:138 offset1:203
	s_waitcnt lgkmcnt(1)
	v_cvt_pk_bf16_f32 v6, v6, v7
	s_waitcnt lgkmcnt(0)
	v_cvt_pk_bf16_f32 v7, v8, v9
	ds_read2_b32 v[8:9], v10 offset0:12 offset1:77
	s_waitcnt lgkmcnt(0)
	v_cvt_pk_bf16_f32 v8, v8, v9
	v_cvt_pk_bf16_f32 v9, v12, v13
	v_add_u32_e32 v12, s3, v11
	v_mov_b64_e32 v[10:11], s[26:27]
	v_mad_i64_i32 v[10:11], s[4:5], v12, s48, v[10:11]
	v_lshl_add_u64 v[10:11], v[10:11], 0, s[40:41]
	v_lshl_add_u64 v[10:11], v[10:11], 0, v[198:199]
	s_mov_b64 s[2:3], 0xddd0000
	v_lshl_add_u64 v[12:13], v[10:11], 0, s[2:3]
	v_add_co_u32_e32 v10, vcc, 0xddd0000, v10
	s_nop 1
	v_addc_co_u32_e32 v11, vcc, 0, v11, vcc
	global_store_dwordx4 v[10:11], v[2:5], off
	global_store_dwordx4 v[12:13], v[6:9], off offset:16
